# r1 next-tile loads de-serialised (d16_hi loads); lnmix gamma/beta/scale/shift kept in AGPRs instead of 16 load-wait round trips per tile
# speedup vs baseline: 1.0216x; 1.0216x over previous
.LBB0_421:
	s_or_b64 exec, exec, s[0:1]
	v_or_b32_e32 v36, 1, v36
	v_cmp_le_i32_e32 vcc, s30, v36
	v_cmp_gt_i32_e64 s[4:5], s31, v36
	s_and_b64 s[4:5], vcc, s[4:5]
	s_and_saveexec_b64 s[0:1], s[4:5]
	s_cbranch_execz .LBB0_423
	v_ashrrev_i32_e32 v37, 31, v36
	v_lshlrev_b64 v[36:37], 10, v[36:37]
	v_lshl_add_u64 v[36:37], v[32:33], 0, v[36:37]
	global_load_short_d16_hi v84, v[36:37], off

.LBB0_425:
	s_or_b64 exec, exec, s[0:1]
	v_or_b32_e32 v36, 1, v34
	v_cmp_le_i32_e32 vcc, s30, v36
	v_cmp_gt_i32_e64 s[4:5], s31, v36
	s_and_b64 s[4:5], vcc, s[4:5]
	s_and_saveexec_b64 s[0:1], s[4:5]
	s_cbranch_execz .LBB0_427
	v_ashrrev_i32_e32 v37, 31, v36
	v_lshlrev_b64 v[36:37], 10, v[36:37]
	v_lshl_add_u64 v[36:37], v[32:33], 0, v[36:37]
	global_load_short_d16_hi v86, v[36:37], off

.LBB0_429:
	s_or_b64 exec, exec, s[0:1]
	v_or_b32_e32 v36, 3, v34
	v_cmp_le_i32_e32 vcc, s30, v36
	v_cmp_gt_i32_e64 s[4:5], s31, v36
	s_and_b64 s[4:5], vcc, s[4:5]
	s_and_saveexec_b64 s[0:1], s[4:5]
	s_cbranch_execz .LBB0_431
	v_ashrrev_i32_e32 v37, 31, v36
	v_lshlrev_b64 v[36:37], 10, v[36:37]
	v_lshl_add_u64 v[36:37], v[32:33], 0, v[36:37]
	global_load_short_d16_hi v106, v[36:37], off

.LBB0_433:
	s_or_b64 exec, exec, s[0:1]
	v_or_b32_e32 v36, 5, v34
	v_cmp_le_i32_e32 vcc, s30, v36
	v_cmp_gt_i32_e64 s[4:5], s31, v36
	s_and_b64 s[4:5], vcc, s[4:5]
	s_and_saveexec_b64 s[0:1], s[4:5]
	s_cbranch_execz .LBB0_435
	v_ashrrev_i32_e32 v37, 31, v36
	v_lshlrev_b64 v[36:37], 10, v[36:37]
	v_lshl_add_u64 v[36:37], v[32:33], 0, v[36:37]
	global_load_short_d16_hi v108, v[36:37], off

.LBB0_437:
	s_or_b64 exec, exec, s[0:1]
	v_or_b32_e32 v36, 7, v34
	v_cmp_le_i32_e32 vcc, s30, v36
	v_cmp_gt_i32_e64 s[4:5], s31, v36
	s_and_b64 s[4:5], vcc, s[4:5]
	s_and_saveexec_b64 s[0:1], s[4:5]
	s_cbranch_execz .LBB0_439
	v_ashrrev_i32_e32 v37, 31, v36
	v_lshlrev_b64 v[36:37], 10, v[36:37]
	v_lshl_add_u64 v[36:37], v[32:33], 0, v[36:37]
	global_load_short_d16_hi v110, v[36:37], off

.LBB0_748:
	s_or_b64 exec, exec, s[0:1]
	s_cmpk_gt_i32 s2, 0x3ff
	s_cbranch_scc1 .LBB0_755
	v_readlane_b32 s8, v126, 2
	v_readlane_b32 s9, v126, 3
	v_readlane_b32 s10, v126, 4
	v_readlane_b32 s11, v126, 5
	v_readlane_b32 s12, v126, 6
	v_readlane_b32 s13, v126, 7
	s_waitcnt vmcnt(14)
	v_and_b32_e32 v6, 63, v2
	v_readlane_b32 s14, v126, 8
	v_readlane_b32 s15, v126, 9
	s_mov_b64 s[8:9], s[12:13]
	v_mov_b32_e32 v1, 0
	s_mov_b64 s[10:11], s[14:15]
	v_lshlrev_b32_e32 v4, 3, v6
	v_mov_b32_e32 v5, v1
	v_mbcnt_lo_u32_b32 v3, -1, 0
	v_lshl_add_u64 v[4:5], s[10:11], 0, v[4:5]
	s_mov_b64 s[0:1], 0x1d3e8000
	v_mbcnt_hi_u32_b32 v3, -1, v3
	v_lshl_add_u64 v[8:9], v[4:5], 0, s[0:1]
	v_and_b32_e32 v4, 64, v3
	v_add_u32_e32 v4, 64, v4
	v_xor_b32_e32 v5, 1, v3
	v_cmp_lt_i32_e32 vcc, v5, v4
	s_add_u32 s12, s10, 0x18e80000
	v_ashrrev_i32_e32 v7, 6, v2
	v_cndmask_b32_e32 v5, v3, v5, vcc
	s_waitcnt vmcnt(5)
	v_lshlrev_b32_e32 v45, 2, v5
	v_xor_b32_e32 v5, 2, v3
	v_cmp_lt_i32_e32 vcc, v5, v4
	s_addc_u32 s13, s11, 0
	v_and_b32_e32 v19, 15, v2
	v_cndmask_b32_e32 v5, v3, v5, vcc
	s_waitcnt vmcnt(4)
	v_lshlrev_b32_e32 v46, 2, v5
	v_xor_b32_e32 v5, 4, v3
	v_cmp_lt_i32_e32 vcc, v5, v4
	v_bfe_u32 v21, v2, 4, 2
	s_add_i32 s0, 0, 0x20100
	v_cndmask_b32_e32 v5, v3, v5, vcc
	v_lshlrev_b32_e32 v47, 2, v5
	v_xor_b32_e32 v5, 8, v3
	v_cmp_lt_i32_e32 vcc, v5, v4
	s_movk_i32 s1, 0x100
	v_lshlrev_b32_e32 v44, 1, v7
	v_cndmask_b32_e32 v5, v3, v5, vcc
	v_lshlrev_b32_e32 v48, 2, v5
	v_xor_b32_e32 v5, 16, v3
	v_cmp_lt_i32_e32 vcc, v5, v4
	v_cmp_gt_i32_e64 s[4:5], s1, v2
	s_waitcnt vmcnt(3)
	v_lshl_add_u32 v52, v2, 2, s0
	v_cndmask_b32_e32 v5, v3, v5, vcc
	v_lshlrev_b32_e32 v49, 2, v5
	v_xor_b32_e32 v5, 32, v3
	v_cmp_lt_i32_e32 vcc, v5, v4
	v_lshlrev_b32_e32 v4, 2, v19
	v_ashrrev_i32_e32 v53, 4, v2
	v_cndmask_b32_e32 v3, v3, v5, vcc
	v_lshlrev_b32_e32 v50, 2, v3
	v_lshl_add_u32 v3, v7, 10, s0
	v_lshlrev_b32_e32 v5, 8, v21
	v_add3_u32 v51, v3, v5, v4
	v_mov_b32_e32 v5, v1
	v_lshl_add_u64 v[2:3], s[10:11], 0, v[4:5]
	s_mov_b64 s[0:1], 0x18fc8000
	v_lshl_add_u64 v[10:11], v[2:3], 0, s[0:1]
	s_movk_i32 s0, 0x2020
	v_lshlrev_b32_e32 v2, 4, v6
	v_mov_b32_e32 v3, v1
	s_waitcnt vmcnt(2)
	v_or_b32_e32 v55, 1, v44
	s_movk_i32 s8, 0x1010
	v_lshlrev_b32_e32 v0, 2, v6
	v_mul_lo_u32 v5, v7, s0
	s_add_i32 s0, 0, 0x10000
	v_lshl_add_u64 v[12:13], s[50:51], 0, v[2:3]
	v_lshl_add_u64 v[14:15], s[52:53], 0, v[2:3]
	v_mul_lo_u32 v3, v55, s8
	v_add3_u32 v54, s0, v5, v2
	v_add3_u32 v56, s0, v3, v2
	v_lshl_add_u64 v[2:3], s[10:11], 0, v[0:1]
	s_mov_b64 s[0:1], 0x1b3e8000
	v_lshl_add_u64 v[16:17], v[2:3], 0, s[0:1]
	v_lshlrev_b32_e32 v1, 13, v7
	v_lshlrev_b32_e32 v2, 6, v21
	v_or3_b32 v57, v1, v2, v4
	v_lshlrev_b32_e32 v1, 9, v7
	v_or_b32_e32 v6, 0x100, v0
	v_or_b32_e32 v18, 0x200, v0
	v_or_b32_e32 v20, 0x300, v0
	v_mad_u32_u24 v1, v19, s8, v1
	v_accvgpr_write_b32 a4, 0
	v_accvgpr_write_b32 a5, 0
	v_accvgpr_write_b32 a6, 0
	s_waitcnt vmcnt(1)
	v_lshl_or_b32 v58, v21, 2, v1
	v_mov_b32_e32 v59, 0x358637bd
	s_mov_b32 s14, 0x800000
	v_lshlrev_b32_e32 v60, 2, v0
	v_lshlrev_b32_e32 v61, 2, v6
	s_waitcnt vmcnt(0)
	v_lshlrev_b32_e32 v62, 2, v18
	v_lshlrev_b32_e32 v63, 2, v20
	s_mov_b32 s15, s2
	global_load_dwordx4 a[8:11], v[12:13], off
	global_load_dwordx4 a[12:15], v[14:15], off
	global_load_dwordx4 a[24:27], v[12:13], off offset:1024
	global_load_dwordx4 a[28:31], v[14:15], off offset:1024
	global_load_dwordx4 a[40:43], v[12:13], off offset:2048
	global_load_dwordx4 a[44:47], v[14:15], off offset:2048
	global_load_dwordx4 a[56:59], v[12:13], off offset:3072
	global_load_dwordx4 a[60:63], v[14:15], off offset:3072
	s_branch .LBB0_751

.LBB0_751:
	s_lshl_b32 s16, s15, 4
	v_add_u32_e32 v24, s16, v44
	v_ashrrev_i32_e32 v25, 31, v24
	v_lshlrev_b64 v[0:1], 11, v[24:25]
	v_lshl_add_u64 v[0:1], v[8:9], 0, v[0:1]
	global_load_dwordx2 v[2:3], v[0:1], off offset:1024
	global_load_dwordx2 v[4:5], v[0:1], off offset:1536
	global_load_dwordx2 v[26:27], v[0:1], off
	global_load_dwordx2 v[32:33], v[0:1], off offset:512
	s_add_i32 s0, s16, 0xffffe000
	s_lshr_b32 s0, s0, 11
	s_add_i32 s0, s0, 1
	s_cmpk_gt_i32 s15, 0x1ff
	s_cselect_b32 s0, s0, 0
	s_mul_hi_u32 s1, s0, 0x6000
	s_mulk_i32 s0, 0x6000
	s_add_u32 s0, s12, s0
	s_addc_u32 s1, s13, s1
	s_add_u32 s8, s0, 0x4000
	s_addc_u32 s9, s1, 0
	s_add_u32 s10, s0, 0x3000
	s_addc_u32 s11, s1, 0
	global_load_dwordx4 a[16:19], v60, s[8:9]
	global_load_dwordx4 a[20:23], v60, s[10:11]
	global_load_dwordx4 a[32:35], v61, s[8:9]
	global_load_dwordx4 a[36:39], v61, s[10:11]
	global_load_dwordx4 a[48:51], v62, s[8:9]
	global_load_dwordx4 a[52:55], v62, s[10:11]
	global_load_dwordx4 a[64:67], v63, s[8:9]
	global_load_dwordx4 a[68:71], v63, s[10:11]
	s_mov_b32 s0, 32
	v_accvgpr_write_b32 a0, 0
	v_accvgpr_mov_b32 a1, a6
	v_accvgpr_mov_b32 a2, a5
	v_accvgpr_mov_b32 a3, a4
	s_waitcnt vmcnt(11)
	v_lshlrev_b32_e32 v20, 16, v2
	v_and_b32_e32 v21, 0xffff0000, v2
	s_waitcnt vmcnt(9)
	v_lshlrev_b32_e32 v29, 16, v27
	v_lshlrev_b32_e32 v28, 16, v26
	v_and_b32_e32 v31, 0xffff0000, v27
	v_and_b32_e32 v30, 0xffff0000, v26
	s_waitcnt vmcnt(8)
	v_lshlrev_b32_e32 v27, 16, v33
	v_lshlrev_b32_e32 v26, 16, v32
	v_and_b32_e32 v33, 0xffff0000, v33
	v_and_b32_e32 v32, 0xffff0000, v32
	v_pk_add_f32 v[34:35], v[28:29], v[30:31]
	v_pk_add_f32 v[36:37], v[26:27], v[32:33]
	v_lshlrev_b32_e32 v22, 16, v3
	v_and_b32_e32 v23, 0xffff0000, v3
	v_and_b32_e32 v3, 0xffff0000, v4
	v_add_f32_e32 v2, v34, v35
	v_pk_add_f32 v[34:35], v[36:37], v[36:37] op_sel:[0,1] op_sel_hi:[1,0]
	v_lshlrev_b32_e32 v7, 16, v4
	v_lshlrev_b32_e32 v19, 16, v5
	v_and_b32_e32 v5, 0xffff0000, v5
	v_add_f32_e32 v18, v20, v21
	v_add_f32_e32 v4, v22, v23
	v_add_f32_e32 v6, 0, v2
	v_mov_b32_e32 v35, v3
	v_pk_add_f32 v[36:37], v[18:19], v[4:5]
	v_pk_add_f32 v[34:35], v[6:7], v[34:35]
	s_nop 0
	v_pk_add_f32 v[34:35], v[34:35], v[36:37]
	s_nop 0
	v_add_f32_e32 v2, v34, v35
	ds_bpermute_b32 v4, v45, v2
	s_waitcnt lgkmcnt(0)
	v_add_f32_e32 v2, v2, v4
	ds_bpermute_b32 v4, v46, v2
	s_waitcnt lgkmcnt(0)
	v_add_f32_e32 v2, v2, v4
	ds_bpermute_b32 v4, v47, v2
	s_waitcnt lgkmcnt(0)
	v_add_f32_e32 v2, v2, v4
	ds_bpermute_b32 v4, v48, v2
	s_waitcnt lgkmcnt(0)
	v_add_f32_e32 v2, v2, v4
	ds_bpermute_b32 v4, v49, v2
	s_waitcnt lgkmcnt(0)
	v_add_f32_e32 v2, v2, v4
	ds_bpermute_b32 v4, v50, v2
	s_waitcnt lgkmcnt(0)
	v_add_f32_e32 v2, v2, v4
	v_fmac_f32_e32 v30, 0xba800000, v2
	v_fmac_f32_e32 v31, 0xba800000, v2
	v_fmac_f32_e32 v29, 0xba800000, v2
	v_fmac_f32_e32 v32, 0xba800000, v2
	v_fmac_f32_e32 v33, 0xba800000, v2
	v_fmac_f32_e32 v27, 0xba800000, v2
	v_fmac_f32_e32 v28, 0xba800000, v2
	v_fmac_f32_e32 v26, 0xba800000, v2
	v_mov_b32_e32 v68, v29
	v_mov_b32_e32 v69, v31
	v_mov_b32_e32 v29, v30
	v_mov_b32_e32 v72, v27
	v_mov_b32_e32 v73, v33
	v_mov_b32_e32 v27, v32
	v_pk_mul_f32 v[30:31], v[68:69], v[68:69]
	v_pk_mul_f32 v[32:33], v[28:29], v[28:29]
	v_pk_mul_f32 v[34:35], v[72:73], v[72:73]
	v_pk_mul_f32 v[36:37], v[26:27], v[26:27]
	v_fmac_f32_e32 v20, 0xba800000, v2
	v_fmac_f32_e32 v22, 0xba800000, v2
	v_pk_mov_b32 v[74:75], v[32:33], v[30:31] op_sel:[1,0]
	v_mov_b32_e32 v33, v31
	v_pk_mov_b32 v[30:31], v[36:37], v[34:35] op_sel:[1,0]
	v_mov_b32_e32 v37, v35
	v_fmac_f32_e32 v21, 0xba800000, v2
	v_fmac_f32_e32 v23, 0xba800000, v2
	v_fmac_f32_e32 v5, 0xba800000, v2
	v_fmac_f32_e32 v19, 0xba800000, v2
	v_fmac_f32_e32 v3, 0xba800000, v2
	v_fmac_f32_e32 v7, 0xba800000, v2
	v_mul_f32_e32 v2, v20, v20
	v_mul_f32_e32 v4, v22, v22
	v_pk_add_f32 v[32:33], v[74:75], v[32:33]
	v_pk_add_f32 v[30:31], v[30:31], v[36:37]
	v_pk_fma_f32 v[38:39], v[20:21], v[20:21], v[2:3] op_sel_hi:[1,1,0]
	v_pk_fma_f32 v[70:71], v[22:23], v[22:23], v[4:5] op_sel_hi:[1,1,0]
	v_pk_add_f32 v[32:33], v[32:33], v[32:33] op_sel_hi:[0,1]
	v_pk_add_f32 v[30:31], v[30:31], v[30:31] op_sel_hi:[0,1]
	v_mul_f32_e32 v38, v7, v7
	v_mul_f32_e32 v70, v3, v3
	v_mul_f32_e32 v32, v19, v19
	v_mul_f32_e32 v30, v5, v5
	v_pk_add_f32 v[34:35], v[38:39], v[70:71]
	v_pk_add_f32 v[30:31], v[32:33], v[30:31]
	s_nop 0
	v_pk_add_f32 v[30:31], v[34:35], v[30:31]
	s_nop 0
	v_add_f32_e32 v2, v30, v31
	ds_bpermute_b32 v4, v45, v2
	v_or_b32_e32 v30, 1, v24
	v_ashrrev_i32_e32 v31, 31, v30
	v_lshlrev_b64 v[30:31], 11, v[30:31]
	v_lshl_add_u64 v[30:31], v[8:9], 0, v[30:31]
	s_waitcnt lgkmcnt(0)
	v_add_f32_e32 v2, v2, v4
	ds_bpermute_b32 v4, v46, v2
	global_load_dwordx2 v[32:33], v[30:31], off
	global_load_dwordx2 v[34:35], v[30:31], off offset:512
	global_load_dwordx2 v[38:39], v[30:31], off offset:1024
	global_load_dwordx2 v[36:37], v[30:31], off offset:1536
	v_lshlrev_b64 v[24:25], 10, v[24:25]
	s_waitcnt lgkmcnt(0)
	v_add_f32_e32 v2, v2, v4
	ds_bpermute_b32 v4, v47, v2
	s_waitcnt lgkmcnt(0)
	v_add_f32_e32 v2, v2, v4
	ds_bpermute_b32 v4, v48, v2
	s_waitcnt lgkmcnt(0)
	v_add_f32_e32 v2, v2, v4
	ds_bpermute_b32 v4, v49, v2
	s_waitcnt lgkmcnt(0)
	v_add_f32_e32 v2, v2, v4
	ds_bpermute_b32 v4, v50, v2
	s_waitcnt lgkmcnt(0)
	v_add_f32_e32 v2, v2, v4
	v_fmamk_f32 v2, v2, 0x3a800000, v59
	v_mul_f32_e32 v4, 0x4b800000, v2
	v_cmp_gt_f32_e32 vcc, s14, v2
	s_nop 1
	v_cndmask_b32_e32 v2, v2, v4, vcc
	v_rsq_f32_e32 v2, v2
	s_nop 0
	v_mul_f32_e32 v4, 0x45800000, v2
	v_cndmask_b32_e32 v6, v2, v4, vcc
	v_pk_mul_f32 v[28:29], v[28:29], v[6:7] op_sel_hi:[1,0]
	v_pk_mul_f32 v[30:31], v[68:69], v[6:7] op_sel_hi:[1,0]
	v_accvgpr_read_b32 v40, a8
	v_accvgpr_read_b32 v41, a9
	v_accvgpr_read_b32 v42, a10
	v_accvgpr_read_b32 v43, a11
	v_accvgpr_read_b32 v64, a12
	v_accvgpr_read_b32 v65, a13
	v_accvgpr_read_b32 v66, a14
	v_accvgpr_read_b32 v67, a15
	s_waitcnt vmcnt(4)
	v_pk_fma_f32 v[28:29], v[40:41], v[28:29], v[64:65]
	v_pk_fma_f32 v[68:69], v[42:43], v[30:31], v[66:67]
	v_cvt_pk_bf16_f32 v30, v28, v29
	v_mov_b32_e32 v2, 0
	v_cvt_pk_bf16_f32 v31, v68, v69
	global_store_dwordx2 v[0:1], v[30:31], off
	v_accvgpr_read_b32 v40, a16
	v_accvgpr_read_b32 v41, a17
	v_accvgpr_read_b32 v42, a18
	v_accvgpr_read_b32 v43, a19
	v_accvgpr_read_b32 v64, a20
	v_accvgpr_read_b32 v65, a21
	v_accvgpr_read_b32 v66, a22
	v_accvgpr_read_b32 v67, a23
	v_lshl_add_u64 v[30:31], v[16:17], 0, v[24:25]
	v_pk_mul_f32 v[20:21], v[20:21], v[6:7] op_sel_hi:[1,0]
	v_pk_mul_f32 v[22:23], v[22:23], v[6:7] op_sel_hi:[1,0]
	v_mov_b32_e32 v4, v19
	v_pk_mul_f32 v[4:5], v[4:5], v[6:7] op_sel_hi:[1,0]
	s_waitcnt vmcnt(1)
	v_and_b32_e32 v19, 0xffff0000, v36
	v_pk_add_f32 v[40:41], v[40:41], 1.0 op_sel_hi:[1,0]
	v_pk_add_f32 v[24:25], v[42:43], 1.0 op_sel_hi:[1,0]
	v_pk_fma_f32 v[40:41], v[40:41], v[28:29], v[64:65]
	v_pk_fma_f32 v[42:43], v[24:25], v[68:69], v[66:67]
	v_cvt_pk_fp8_f32 v2, v40, v41
	v_pk_mul_f32 v[24:25], v[26:27], v[6:7] op_sel_hi:[1,0]
	v_cvt_pk_fp8_f32 v2, v42, v43 op_sel:[0,0,1]
	global_store_dword v[30:31], v2, off
	v_accvgpr_read_b32 v64, a24
	v_accvgpr_read_b32 v65, a25
	v_accvgpr_read_b32 v66, a26
	v_accvgpr_read_b32 v67, a27
	v_accvgpr_read_b32 v68, a28
	v_accvgpr_read_b32 v69, a29
	v_accvgpr_read_b32 v70, a30
	v_accvgpr_read_b32 v71, a31
	v_pk_mul_f32 v[26:27], v[72:73], v[6:7] op_sel_hi:[1,0]
	ds_write_b128 v54, v[40:43]
	v_mov_b32_e32 v2, 0
	v_pk_fma_f32 v[28:29], v[66:67], v[26:27], v[70:71]
	v_pk_fma_f32 v[64:65], v[64:65], v[24:25], v[68:69]
	s_nop 0
	v_cvt_pk_bf16_f32 v24, v64, v65
	v_cvt_pk_bf16_f32 v25, v28, v29
	global_store_dwordx2 v[0:1], v[24:25], off offset:512
	v_accvgpr_read_b32 v24, a32
	v_accvgpr_read_b32 v25, a33
	v_accvgpr_read_b32 v26, a34
	v_accvgpr_read_b32 v27, a35
	s_nop 0
	v_accvgpr_read_b32 v40, a36
	v_accvgpr_read_b32 v41, a37
	v_accvgpr_read_b32 v42, a38
	v_accvgpr_read_b32 v43, a39
	v_pk_add_f32 v[24:25], v[24:25], 1.0 op_sel_hi:[1,0]
	v_pk_add_f32 v[26:27], v[26:27], 1.0 op_sel_hi:[1,0]
	v_pk_fma_f32 v[24:25], v[24:25], v[64:65], v[40:41]
	v_pk_fma_f32 v[26:27], v[26:27], v[28:29], v[42:43]
	v_cvt_pk_fp8_f32 v2, v24, v25
	s_nop 0
	v_cvt_pk_fp8_f32 v2, v26, v27 op_sel:[0,0,1]
	global_store_dword v[30:31], v2, off offset:256
	v_accvgpr_read_b32 v40, a40
	v_accvgpr_read_b32 v41, a41
	v_accvgpr_read_b32 v42, a42
	v_accvgpr_read_b32 v43, a43
	v_accvgpr_read_b32 v64, a44
	v_accvgpr_read_b32 v65, a45
	v_accvgpr_read_b32 v66, a46
	v_accvgpr_read_b32 v67, a47
	ds_write_b128 v54, v[24:27] offset:1024
	v_mov_b32_e32 v2, 0
	v_pk_fma_f32 v[28:29], v[22:23], v[42:43], v[66:67]
	v_pk_fma_f32 v[40:41], v[20:21], v[40:41], v[64:65]
	s_nop 0
	v_cvt_pk_bf16_f32 v20, v40, v41
	v_cvt_pk_bf16_f32 v21, v28, v29
	global_store_dwordx2 v[0:1], v[20:21], off offset:1024
	v_accvgpr_read_b32 v20, a48
	v_accvgpr_read_b32 v21, a49
	v_accvgpr_read_b32 v22, a50
	v_accvgpr_read_b32 v23, a51
	s_nop 0
	v_accvgpr_read_b32 v24, a52
	v_accvgpr_read_b32 v25, a53
	v_accvgpr_read_b32 v26, a54
	v_accvgpr_read_b32 v27, a55
	v_pk_add_f32 v[20:21], v[20:21], 1.0 op_sel_hi:[1,0]
	v_pk_add_f32 v[22:23], v[22:23], 1.0 op_sel_hi:[1,0]
	v_pk_fma_f32 v[20:21], v[40:41], v[20:21], v[24:25]
	v_pk_fma_f32 v[22:23], v[28:29], v[22:23], v[26:27]
	v_cvt_pk_fp8_f32 v2, v20, v21
	v_lshlrev_b32_e32 v26, 16, v38
	v_cvt_pk_fp8_f32 v2, v22, v23 op_sel:[0,0,1]
	global_store_dword v[30:31], v2, off offset:512
	v_accvgpr_read_b32 v64, a56
	v_accvgpr_read_b32 v65, a57
	v_accvgpr_read_b32 v66, a58
	v_accvgpr_read_b32 v67, a59
	v_accvgpr_read_b32 v68, a60
	v_accvgpr_read_b32 v69, a61
	v_accvgpr_read_b32 v70, a62
	v_accvgpr_read_b32 v71, a63
	v_mov_b32_e32 v2, v7
	v_pk_mul_f32 v[2:3], v[2:3], v[6:7] op_sel_hi:[1,0]
	ds_write_b128 v54, v[20:23] offset:2048
	v_and_b32_e32 v27, 0xffff0000, v38
	v_lshlrev_b32_e32 v28, 16, v39
	v_and_b32_e32 v29, 0xffff0000, v39
	v_lshlrev_b32_e32 v23, 16, v36
	v_lshlrev_b32_e32 v25, 16, v37
	v_and_b32_e32 v21, 0xffff0000, v37
	v_lshlrev_b32_e32 v37, 16, v33
	v_lshlrev_b32_e32 v36, 16, v32
	v_and_b32_e32 v39, 0xffff0000, v33
	v_and_b32_e32 v38, 0xffff0000, v32
	v_lshlrev_b32_e32 v33, 16, v35
	v_lshlrev_b32_e32 v32, 16, v34
	v_and_b32_e32 v35, 0xffff0000, v35
	v_and_b32_e32 v34, 0xffff0000, v34
	v_add_f32_e32 v24, v26, v27
	v_add_f32_e32 v20, v28, v29
	v_pk_fma_f32 v[40:41], v[4:5], v[66:67], v[70:71]
	v_pk_fma_f32 v[42:43], v[2:3], v[64:65], v[68:69]
	v_pk_add_f32 v[64:65], v[36:37], v[38:39]
	v_cvt_pk_bf16_f32 v2, v42, v43
	v_cvt_pk_bf16_f32 v3, v40, v41
	global_store_dwordx2 v[0:1], v[2:3], off offset:1536
	v_accvgpr_read_b32 v0, a64
	v_accvgpr_read_b32 v1, a65
	v_accvgpr_read_b32 v2, a66
	v_accvgpr_read_b32 v3, a67
	v_pk_add_f32 v[66:67], v[32:33], v[34:35]
	v_accvgpr_read_b32 v4, a68
	v_accvgpr_read_b32 v5, a69
	v_accvgpr_read_b32 v6, a70
	v_accvgpr_read_b32 v7, a71
	v_add_f32_e32 v18, v64, v65
	v_pk_add_f32 v[64:65], v[66:67], v[66:67] op_sel:[0,1] op_sel_hi:[1,0]
	v_add_f32_e32 v22, 0, v18
	v_mov_b32_e32 v65, v19
	v_pk_add_f32 v[66:67], v[24:25], v[20:21]
	v_pk_add_f32 v[64:65], v[22:23], v[64:65]
	v_mov_b32_e32 v22, 0
	v_pk_add_f32 v[64:65], v[64:65], v[66:67]
	v_pk_add_f32 v[0:1], v[0:1], 1.0 op_sel_hi:[1,0]
	v_add_f32_e32 v18, v64, v65
	ds_bpermute_b32 v20, v45, v18
	v_pk_add_f32 v[2:3], v[2:3], 1.0 op_sel_hi:[1,0]
	v_pk_fma_f32 v[64:65], v[42:43], v[0:1], v[4:5]
	v_pk_fma_f32 v[66:67], v[40:41], v[2:3], v[6:7]
	v_cvt_pk_fp8_f32 v22, v64, v65
	s_waitcnt lgkmcnt(0)
	v_add_f32_e32 v18, v18, v20
	ds_bpermute_b32 v20, v46, v18
	v_cvt_pk_fp8_f32 v22, v66, v67 op_sel:[0,0,1]
	global_store_dword v[30:31], v22, off offset:768
	v_accvgpr_read_b32 v40, a8
	v_accvgpr_read_b32 v41, a9
	v_accvgpr_read_b32 v42, a10
	v_accvgpr_read_b32 v43, a11
	v_accvgpr_read_b32 v68, a12
	v_accvgpr_read_b32 v69, a13
	v_accvgpr_read_b32 v70, a14
	v_accvgpr_read_b32 v71, a15
	ds_write_b128 v54, v[64:67] offset:3072
	s_waitcnt lgkmcnt(1)
	v_add_f32_e32 v18, v18, v20
	ds_bpermute_b32 v20, v47, v18
	s_waitcnt lgkmcnt(0)
	v_add_f32_e32 v18, v18, v20
	ds_bpermute_b32 v20, v48, v18
	s_waitcnt lgkmcnt(0)
	v_add_f32_e32 v18, v18, v20
	ds_bpermute_b32 v20, v49, v18
	s_waitcnt lgkmcnt(0)
	v_add_f32_e32 v18, v18, v20
	ds_bpermute_b32 v20, v50, v18
	s_waitcnt lgkmcnt(0)
	v_add_f32_e32 v18, v18, v20
	v_fmac_f32_e32 v38, 0xba800000, v18
	v_fmac_f32_e32 v39, 0xba800000, v18
	v_fmac_f32_e32 v37, 0xba800000, v18
	v_fmac_f32_e32 v34, 0xba800000, v18
	v_fmac_f32_e32 v35, 0xba800000, v18
	v_fmac_f32_e32 v33, 0xba800000, v18
	v_fmac_f32_e32 v36, 0xba800000, v18
	v_fmac_f32_e32 v32, 0xba800000, v18
	v_fmac_f32_e32 v26, 0xba800000, v18
	v_fmac_f32_e32 v28, 0xba800000, v18
	v_mov_b32_e32 v0, v37
	v_mov_b32_e32 v1, v39
	v_mov_b32_e32 v37, v38
	v_mov_b32_e32 v6, v33
	v_mov_b32_e32 v7, v35
	v_mov_b32_e32 v33, v34
	v_fmac_f32_e32 v27, 0xba800000, v18
	v_fmac_f32_e32 v29, 0xba800000, v18
	v_mul_f32_e32 v2, v26, v26
	v_mul_f32_e32 v4, v28, v28
	v_pk_mul_f32 v[30:31], v[0:1], v[0:1]
	v_pk_mul_f32 v[34:35], v[36:37], v[36:37]
	v_pk_mul_f32 v[38:39], v[6:7], v[6:7]
	v_pk_mul_f32 v[72:73], v[32:33], v[32:33]
	v_fmac_f32_e32 v19, 0xba800000, v18
	v_fmac_f32_e32 v23, 0xba800000, v18
	v_pk_fma_f32 v[2:3], v[26:27], v[26:27], v[2:3] op_sel_hi:[1,1,0]
	v_pk_fma_f32 v[4:5], v[28:29], v[28:29], v[4:5] op_sel_hi:[1,1,0]
	v_pk_mov_b32 v[74:75], v[34:35], v[30:31] op_sel:[1,0]
	v_mov_b32_e32 v35, v31
	v_pk_mov_b32 v[30:31], v[72:73], v[38:39] op_sel:[1,0]
	v_mov_b32_e32 v73, v39
	v_mul_f32_e32 v2, v23, v23
	v_mul_f32_e32 v4, v19, v19
	v_pk_add_f32 v[34:35], v[74:75], v[34:35]
	v_pk_add_f32 v[30:31], v[30:31], v[72:73]
	v_fmac_f32_e32 v21, 0xba800000, v18
	v_fmac_f32_e32 v25, 0xba800000, v18
	v_pk_add_f32 v[2:3], v[2:3], v[4:5]
	v_pk_add_f32 v[4:5], v[34:35], v[34:35] op_sel_hi:[0,1]
	v_pk_add_f32 v[30:31], v[30:31], v[30:31] op_sel_hi:[0,1]
	v_mul_f32_e32 v4, v25, v25
	v_mul_f32_e32 v30, v21, v21
	v_pk_add_f32 v[4:5], v[4:5], v[30:31]
	v_add_u32_e32 v30, s16, v55
	v_pk_add_f32 v[2:3], v[2:3], v[4:5]
	v_ashrrev_i32_e32 v31, 31, v30
	v_add_f32_e32 v2, v2, v3
	ds_bpermute_b32 v3, v45, v2
	v_mov_b32_e32 v18, v23
	v_mov_b32_e32 v20, v25
	s_waitcnt lgkmcnt(0)
	v_add_f32_e32 v2, v2, v3
	ds_bpermute_b32 v3, v46, v2
	s_waitcnt lgkmcnt(0)
	v_add_f32_e32 v2, v2, v3
	ds_bpermute_b32 v3, v47, v2
	s_waitcnt lgkmcnt(0)
	v_add_f32_e32 v2, v2, v3
	ds_bpermute_b32 v3, v48, v2
	s_waitcnt lgkmcnt(0)
	v_add_f32_e32 v2, v2, v3
	ds_bpermute_b32 v3, v49, v2
	s_waitcnt lgkmcnt(0)
	v_add_f32_e32 v2, v2, v3
	ds_bpermute_b32 v3, v50, v2
	s_waitcnt lgkmcnt(0)
	v_add_f32_e32 v2, v2, v3
	v_fmamk_f32 v2, v2, 0x3a800000, v59
	v_mul_f32_e32 v3, 0x4b800000, v2
	v_cmp_gt_f32_e32 vcc, s14, v2
	s_nop 1
	v_cndmask_b32_e32 v2, v2, v3, vcc
	v_rsq_f32_e32 v4, v2
	v_lshlrev_b64 v[2:3], 11, v[30:31]
	v_lshl_add_u64 v[2:3], v[8:9], 0, v[2:3]
	v_mul_f32_e32 v5, 0x45800000, v4
	v_cndmask_b32_e32 v4, v4, v5, vcc
	v_pk_mul_f32 v[34:35], v[36:37], v[4:5] op_sel_hi:[1,0]
	v_pk_mul_f32 v[0:1], v[0:1], v[4:5] op_sel_hi:[1,0]
	v_pk_fma_f32 v[64:65], v[40:41], v[34:35], v[68:69]
	v_pk_fma_f32 v[42:43], v[42:43], v[0:1], v[70:71]
	v_cvt_pk_bf16_f32 v0, v64, v65
	v_mov_b32_e32 v5, 0
	v_cvt_pk_bf16_f32 v1, v42, v43
	global_store_dwordx2 v[2:3], v[0:1], off
	v_accvgpr_read_b32 v34, a16
	v_accvgpr_read_b32 v35, a17
	v_accvgpr_read_b32 v36, a18
	v_accvgpr_read_b32 v37, a19
	v_accvgpr_read_b32 v38, a20
	v_accvgpr_read_b32 v39, a21
	v_accvgpr_read_b32 v40, a22
	v_accvgpr_read_b32 v41, a23
	v_lshlrev_b64 v[0:1], 10, v[30:31]
	v_lshl_add_u64 v[0:1], v[16:17], 0, v[0:1]
	v_pk_add_f32 v[34:35], v[34:35], 1.0 op_sel_hi:[1,0]
	v_pk_add_f32 v[30:31], v[36:37], 1.0 op_sel_hi:[1,0]
	v_pk_fma_f32 v[34:35], v[34:35], v[64:65], v[38:39]
	v_pk_fma_f32 v[36:37], v[30:31], v[42:43], v[40:41]
	v_cvt_pk_fp8_f32 v5, v34, v35
	s_nop 0
	v_cvt_pk_fp8_f32 v5, v36, v37 op_sel:[0,0,1]
	global_store_dword v[0:1], v5, off
	v_accvgpr_read_b32 v38, a24
	v_accvgpr_read_b32 v39, a25
	v_accvgpr_read_b32 v40, a26
	v_accvgpr_read_b32 v41, a27
	v_accvgpr_read_b32 v64, a28
	v_accvgpr_read_b32 v65, a29
	v_accvgpr_read_b32 v66, a30
	v_accvgpr_read_b32 v67, a31
	v_pk_mul_f32 v[30:31], v[32:33], v[4:5] op_sel_hi:[1,0]
	v_pk_mul_f32 v[6:7], v[6:7], v[4:5] op_sel_hi:[1,0]
	ds_write_b128 v56, v[34:37]
	v_mov_b32_e32 v5, 0
	v_pk_fma_f32 v[6:7], v[40:41], v[6:7], v[66:67]
	v_pk_fma_f32 v[38:39], v[38:39], v[30:31], v[64:65]
	s_nop 0
	v_cvt_pk_bf16_f32 v30, v38, v39
	v_cvt_pk_bf16_f32 v31, v6, v7
	global_store_dwordx2 v[2:3], v[30:31], off offset:512
	v_accvgpr_read_b32 v30, a32
	v_accvgpr_read_b32 v31, a33
	v_accvgpr_read_b32 v32, a34
	v_accvgpr_read_b32 v33, a35
	s_nop 0
	v_accvgpr_read_b32 v34, a36
	v_accvgpr_read_b32 v35, a37
	v_accvgpr_read_b32 v36, a38
	v_accvgpr_read_b32 v37, a39
	v_pk_add_f32 v[30:31], v[30:31], 1.0 op_sel_hi:[1,0]
	v_pk_add_f32 v[32:33], v[32:33], 1.0 op_sel_hi:[1,0]
	v_pk_fma_f32 v[30:31], v[30:31], v[38:39], v[34:35]
	v_pk_fma_f32 v[32:33], v[32:33], v[6:7], v[36:37]
	v_cvt_pk_fp8_f32 v5, v30, v31
	s_nop 0
	v_cvt_pk_fp8_f32 v5, v32, v33 op_sel:[0,0,1]
	global_store_dword v[0:1], v5, off offset:256
	v_accvgpr_read_b32 v34, a40
	v_accvgpr_read_b32 v35, a41
	v_accvgpr_read_b32 v36, a42
	v_accvgpr_read_b32 v37, a43
	v_accvgpr_read_b32 v38, a44
	v_accvgpr_read_b32 v39, a45
	v_accvgpr_read_b32 v40, a46
	v_accvgpr_read_b32 v41, a47
	v_pk_mul_f32 v[6:7], v[26:27], v[4:5] op_sel_hi:[1,0]
	v_pk_mul_f32 v[26:27], v[28:29], v[4:5] op_sel_hi:[1,0]
	ds_write_b128 v56, v[30:33] offset:1024
	v_mov_b32_e32 v5, 0
	v_pk_fma_f32 v[36:37], v[26:27], v[36:37], v[40:41]
	v_pk_fma_f32 v[6:7], v[6:7], v[34:35], v[38:39]
	s_nop 0
	v_cvt_pk_bf16_f32 v26, v6, v7
	v_cvt_pk_bf16_f32 v27, v36, v37
	global_store_dwordx2 v[2:3], v[26:27], off offset:1024
	v_accvgpr_read_b32 v26, a48
	v_accvgpr_read_b32 v27, a49
	v_accvgpr_read_b32 v28, a50
	v_accvgpr_read_b32 v29, a51
	s_nop 0
	v_accvgpr_read_b32 v30, a52
	v_accvgpr_read_b32 v31, a53
	v_accvgpr_read_b32 v32, a54
	v_accvgpr_read_b32 v33, a55
	v_pk_add_f32 v[26:27], v[26:27], 1.0 op_sel_hi:[1,0]
	v_pk_add_f32 v[28:29], v[28:29], 1.0 op_sel_hi:[1,0]
	v_pk_fma_f32 v[26:27], v[6:7], v[26:27], v[30:31]
	v_pk_fma_f32 v[28:29], v[36:37], v[28:29], v[32:33]
	v_cvt_pk_fp8_f32 v5, v26, v27
	s_nop 0
	v_cvt_pk_fp8_f32 v5, v28, v29 op_sel:[0,0,1]
	global_store_dword v[0:1], v5, off offset:512
	v_accvgpr_read_b32 v30, a56
	v_accvgpr_read_b32 v31, a57
	v_accvgpr_read_b32 v32, a58
	v_accvgpr_read_b32 v33, a59
	v_accvgpr_read_b32 v34, a60
	v_accvgpr_read_b32 v35, a61
	v_accvgpr_read_b32 v36, a62
	v_accvgpr_read_b32 v37, a63
	v_pk_mul_f32 v[6:7], v[18:19], v[4:5] op_sel_hi:[1,0]
	v_pk_mul_f32 v[4:5], v[20:21], v[4:5] op_sel_hi:[1,0]
	ds_write_b128 v56, v[26:29] offset:2048
	v_mov_b32_e32 v26, 0
	v_pk_fma_f32 v[22:23], v[4:5], v[32:33], v[36:37]
	v_pk_fma_f32 v[24:25], v[6:7], v[30:31], v[34:35]
	s_nop 0
	v_cvt_pk_bf16_f32 v4, v24, v25
	v_cvt_pk_bf16_f32 v5, v22, v23
	global_store_dwordx2 v[2:3], v[4:5], off offset:1536
	v_accvgpr_read_b32 v4, a64
	v_accvgpr_read_b32 v5, a65
	v_accvgpr_read_b32 v6, a66
	v_accvgpr_read_b32 v7, a67
	s_nop 0
	v_accvgpr_read_b32 v18, a68
	v_accvgpr_read_b32 v19, a69
	v_accvgpr_read_b32 v20, a70
	v_accvgpr_read_b32 v21, a71
	v_mov_b32_e32 v2, v58
	v_mov_b32_e32 v3, v57
	v_pk_add_f32 v[6:7], v[6:7], 1.0 op_sel_hi:[1,0]
	v_pk_add_f32 v[4:5], v[4:5], 1.0 op_sel_hi:[1,0]
	v_pk_fma_f32 v[6:7], v[22:23], v[6:7], v[20:21]
	v_pk_fma_f32 v[4:5], v[24:25], v[4:5], v[18:19]
	s_nop 0
	v_cvt_pk_fp8_f32 v26, v4, v5
	s_nop 0
	v_cvt_pk_fp8_f32 v26, v6, v7 op_sel:[0,0,1]
	ds_write_b128 v56, v[4:7] offset:3072
	global_store_dword v[0:1], v26, off offset:768
	s_waitcnt lgkmcnt(0)
	s_barrier

.LBB0_1349:
	s_or_b64 exec, exec, s[0:1]
	s_cmpk_gt_i32 s2, 0x3ff
	s_cbranch_scc1 .LBB0_1356
	v_readlane_b32 s12, v126, 2
	v_readlane_b32 s13, v126, 3
	v_readlane_b32 s14, v126, 4
	v_readlane_b32 s15, v126, 5
	v_readlane_b32 s16, v126, 6
	v_readlane_b32 s17, v126, 7
	v_and_b32_e32 v6, 63, v2
	v_readlane_b32 s18, v126, 8
	v_readlane_b32 s19, v126, 9
	s_mov_b64 s[12:13], s[16:17]
	v_mov_b32_e32 v1, 0
	s_mov_b64 s[14:15], s[18:19]
	v_lshlrev_b32_e32 v4, 3, v6
	v_mov_b32_e32 v5, v1
	v_mbcnt_lo_u32_b32 v3, -1, 0
	v_lshl_add_u64 v[4:5], s[14:15], 0, v[4:5]
	s_mov_b64 s[4:5], 0x1d3e8000
	v_mbcnt_hi_u32_b32 v3, -1, v3
	v_lshl_add_u64 v[8:9], v[4:5], 0, s[4:5]
	v_and_b32_e32 v4, 64, v3
	v_add_u32_e32 v4, 64, v4
	v_xor_b32_e32 v5, 1, v3
	v_cmp_lt_i32_e32 vcc, v5, v4
	s_add_u32 s0, s52, 0x1000
	s_addc_u32 s1, s53, 0
	v_cndmask_b32_e32 v5, v3, v5, vcc
	v_lshlrev_b32_e32 v57, 2, v5
	v_xor_b32_e32 v5, 2, v3
	v_cmp_lt_i32_e32 vcc, v5, v4
	s_add_u32 s8, s50, 0x1000
	s_addc_u32 s9, s51, 0
	v_cndmask_b32_e32 v5, v3, v5, vcc
	v_lshlrev_b32_e32 v58, 2, v5
	v_xor_b32_e32 v5, 4, v3
	v_cmp_lt_i32_e32 vcc, v5, v4
	s_add_u32 s12, s14, 0x18e80000
	v_ashrrev_i32_e32 v7, 6, v2
	v_cndmask_b32_e32 v5, v3, v5, vcc
	v_lshlrev_b32_e32 v59, 2, v5
	v_xor_b32_e32 v5, 8, v3
	v_cmp_lt_i32_e32 vcc, v5, v4
	s_addc_u32 s13, s15, 0
	v_and_b32_e32 v31, 15, v2
	v_cndmask_b32_e32 v5, v3, v5, vcc
	v_lshlrev_b32_e32 v60, 2, v5
	v_xor_b32_e32 v5, 16, v3
	v_cmp_lt_i32_e32 vcc, v5, v4
	v_bfe_u32 v33, v2, 4, 2
	s_add_i32 s10, 0, 0x20100
	v_cndmask_b32_e32 v5, v3, v5, vcc
	v_lshlrev_b32_e32 v61, 2, v5
	v_xor_b32_e32 v5, 32, v3
	v_cmp_lt_i32_e32 vcc, v5, v4
	v_lshlrev_b32_e32 v4, 2, v31
	s_movk_i32 s4, 0x100
	v_cndmask_b32_e32 v3, v3, v5, vcc
	v_lshlrev_b32_e32 v62, 2, v3
	v_lshl_add_u32 v3, v7, 10, s10
	v_lshlrev_b32_e32 v5, 8, v33
	v_add3_u32 v63, v3, v5, v4
	v_mov_b32_e32 v5, v1
	v_lshlrev_b32_e32 v0, 2, v6
	v_cmp_gt_i32_e64 s[4:5], s4, v2
	v_lshl_add_u32 v64, v2, 2, s10
	v_ashrrev_i32_e32 v65, 4, v2
	v_lshl_add_u64 v[2:3], s[14:15], 0, v[4:5]
	s_mov_b64 s[10:11], 0x18fc8000
	v_lshl_add_u64 v[10:11], v[2:3], 0, s[10:11]
	v_lshlrev_b32_e32 v2, 4, v6
	v_or_b32_e32 v6, 0x100, v0
	v_or_b32_e32 v30, 0x200, v0
	v_or_b32_e32 v32, 0x300, v0
	v_lshlrev_b32_e32 v56, 1, v7
	v_mov_b32_e32 v3, v1
	v_lshlrev_b32_e32 v18, 2, v6
	v_mov_b32_e32 v19, v1
	v_lshlrev_b32_e32 v22, 2, v30
	v_mov_b32_e32 v23, v1
	v_lshlrev_b32_e32 v26, 2, v32
	v_mov_b32_e32 v27, v1
	s_movk_i32 s10, 0x2020
	v_lshl_add_u64 v[12:13], s[8:9], 0, v[2:3]
	v_lshl_add_u64 v[16:17], s[8:9], 0, v[18:19]
	v_lshl_add_u64 v[20:21], s[8:9], 0, v[22:23]
	v_lshl_add_u64 v[24:25], s[8:9], 0, v[26:27]
	v_or_b32_e32 v67, 1, v56
	s_movk_i32 s8, 0x1010
	v_mul_lo_u32 v5, v7, s10
	s_add_i32 s10, 0, 0x10000
	v_lshl_add_u64 v[14:15], s[0:1], 0, v[2:3]
	v_mul_lo_u32 v3, v67, s8
	v_add3_u32 v66, s10, v5, v2
	v_lshl_add_u64 v[18:19], s[0:1], 0, v[18:19]
	v_lshl_add_u64 v[22:23], s[0:1], 0, v[22:23]
	v_lshl_add_u64 v[26:27], s[0:1], 0, v[26:27]
	v_add3_u32 v68, s10, v3, v2
	v_lshl_add_u64 v[2:3], s[14:15], 0, v[0:1]
	s_mov_b64 s[0:1], 0x1b3e8000
	v_lshl_add_u64 v[28:29], v[2:3], 0, s[0:1]
	v_lshlrev_b32_e32 v1, 13, v7
	v_lshlrev_b32_e32 v2, 6, v33
	v_or3_b32 v69, v1, v2, v4
	v_lshlrev_b32_e32 v1, 9, v7
	v_mad_u32_u24 v1, v31, s8, v1
	v_accvgpr_write_b32 a4, 0
	v_accvgpr_write_b32 a5, 0
	v_accvgpr_write_b32 a6, 0
	v_lshl_or_b32 v70, v33, 2, v1
	v_mov_b32_e32 v71, 0x358637bd
	s_mov_b32 s14, 0x800000
	v_lshlrev_b32_e32 v72, 2, v0
	v_lshlrev_b32_e32 v73, 2, v6
	v_lshlrev_b32_e32 v74, 2, v30
	v_lshlrev_b32_e32 v75, 2, v32
	s_mov_b32 s15, s2
	global_load_dwordx4 a[8:11], v[12:13], off
	global_load_dwordx4 a[12:15], v[14:15], off
	global_load_dwordx4 a[24:27], v[16:17], off
	global_load_dwordx4 a[28:31], v[18:19], off
	global_load_dwordx4 a[40:43], v[20:21], off
	global_load_dwordx4 a[44:47], v[22:23], off
	global_load_dwordx4 a[56:59], v[24:25], off
	global_load_dwordx4 a[60:63], v[26:27], off
	s_branch .LBB0_1352

.LBB0_1352:
	s_lshl_b32 s16, s15, 4
	v_add_u32_e32 v36, s16, v56
	v_ashrrev_i32_e32 v37, 31, v36
	v_lshlrev_b64 v[0:1], 11, v[36:37]
	v_lshl_add_u64 v[0:1], v[8:9], 0, v[0:1]
	global_load_dwordx2 v[2:3], v[0:1], off offset:1024
	global_load_dwordx2 v[4:5], v[0:1], off offset:1536
	global_load_dwordx2 v[38:39], v[0:1], off
	global_load_dwordx2 v[44:45], v[0:1], off offset:512
	s_add_i32 s0, s16, 0xffffe000
	s_lshr_b32 s0, s0, 11
	s_add_i32 s0, s0, 6
	s_cmpk_gt_i32 s15, 0x1ff
	s_cselect_b32 s0, s0, 5
	s_mul_hi_u32 s1, s0, 0x6000
	s_mulk_i32 s0, 0x6000
	s_add_u32 s0, s12, s0
	s_addc_u32 s1, s13, s1
	s_add_u32 s10, s0, 0x4000
	s_addc_u32 s11, s1, 0
	s_add_u32 s8, s0, 0x3000
	s_addc_u32 s9, s1, 0
	global_load_dwordx4 a[16:19], v72, s[10:11]
	global_load_dwordx4 a[20:23], v72, s[8:9]
	global_load_dwordx4 a[32:35], v73, s[10:11]
	global_load_dwordx4 a[36:39], v73, s[8:9]
	global_load_dwordx4 a[48:51], v74, s[10:11]
	global_load_dwordx4 a[52:55], v74, s[8:9]
	global_load_dwordx4 a[64:67], v75, s[10:11]
	global_load_dwordx4 a[68:71], v75, s[8:9]
	s_mov_b32 s0, 32
	v_accvgpr_write_b32 a0, 0
	v_accvgpr_mov_b32 a1, a6
	v_accvgpr_mov_b32 a2, a5
	v_accvgpr_mov_b32 a3, a4
	s_waitcnt vmcnt(11)
	v_lshlrev_b32_e32 v32, 16, v2
	v_and_b32_e32 v33, 0xffff0000, v2
	s_waitcnt vmcnt(9)
	v_lshlrev_b32_e32 v41, 16, v39
	v_lshlrev_b32_e32 v40, 16, v38
	v_and_b32_e32 v43, 0xffff0000, v39
	v_and_b32_e32 v42, 0xffff0000, v38
	s_waitcnt vmcnt(8)
	v_lshlrev_b32_e32 v39, 16, v45
	v_lshlrev_b32_e32 v38, 16, v44
	v_and_b32_e32 v45, 0xffff0000, v45
	v_and_b32_e32 v44, 0xffff0000, v44
	v_pk_add_f32 v[46:47], v[40:41], v[42:43]
	v_pk_add_f32 v[48:49], v[38:39], v[44:45]
	v_lshlrev_b32_e32 v34, 16, v3
	v_and_b32_e32 v35, 0xffff0000, v3
	v_and_b32_e32 v3, 0xffff0000, v4
	v_add_f32_e32 v2, v46, v47
	v_pk_add_f32 v[46:47], v[48:49], v[48:49] op_sel:[0,1] op_sel_hi:[1,0]
	v_lshlrev_b32_e32 v7, 16, v4
	v_lshlrev_b32_e32 v31, 16, v5
	v_and_b32_e32 v5, 0xffff0000, v5
	v_add_f32_e32 v30, v32, v33
	v_add_f32_e32 v4, v34, v35
	v_add_f32_e32 v6, 0, v2
	v_mov_b32_e32 v47, v3
	v_pk_add_f32 v[48:49], v[30:31], v[4:5]
	v_pk_add_f32 v[46:47], v[6:7], v[46:47]
	s_nop 0
	v_pk_add_f32 v[46:47], v[46:47], v[48:49]
	s_nop 0
	v_add_f32_e32 v2, v46, v47
	ds_bpermute_b32 v4, v57, v2
	s_waitcnt lgkmcnt(0)
	v_add_f32_e32 v2, v2, v4
	ds_bpermute_b32 v4, v58, v2
	s_waitcnt lgkmcnt(0)
	v_add_f32_e32 v2, v2, v4
	ds_bpermute_b32 v4, v59, v2
	s_waitcnt lgkmcnt(0)
	v_add_f32_e32 v2, v2, v4
	ds_bpermute_b32 v4, v60, v2
	s_waitcnt lgkmcnt(0)
	v_add_f32_e32 v2, v2, v4
	ds_bpermute_b32 v4, v61, v2
	s_waitcnt lgkmcnt(0)
	v_add_f32_e32 v2, v2, v4
	ds_bpermute_b32 v4, v62, v2
	s_waitcnt lgkmcnt(0)
	v_add_f32_e32 v2, v2, v4
	v_fmac_f32_e32 v42, 0xba800000, v2
	v_fmac_f32_e32 v43, 0xba800000, v2
	v_fmac_f32_e32 v41, 0xba800000, v2
	v_fmac_f32_e32 v44, 0xba800000, v2
	v_fmac_f32_e32 v45, 0xba800000, v2
	v_fmac_f32_e32 v39, 0xba800000, v2
	v_fmac_f32_e32 v40, 0xba800000, v2
	v_fmac_f32_e32 v38, 0xba800000, v2
	v_mov_b32_e32 v82, v41
	v_mov_b32_e32 v83, v43
	v_mov_b32_e32 v41, v42
	v_mov_b32_e32 v86, v39
	v_mov_b32_e32 v87, v45
	v_mov_b32_e32 v39, v44
	v_pk_mul_f32 v[42:43], v[82:83], v[82:83]
	v_pk_mul_f32 v[44:45], v[40:41], v[40:41]
	v_pk_mul_f32 v[46:47], v[86:87], v[86:87]
	v_pk_mul_f32 v[48:49], v[38:39], v[38:39]
	v_fmac_f32_e32 v32, 0xba800000, v2
	v_fmac_f32_e32 v34, 0xba800000, v2
	v_pk_mov_b32 v[88:89], v[44:45], v[42:43] op_sel:[1,0]
	v_mov_b32_e32 v45, v43
	v_pk_mov_b32 v[42:43], v[48:49], v[46:47] op_sel:[1,0]
	v_mov_b32_e32 v49, v47
	v_fmac_f32_e32 v33, 0xba800000, v2
	v_fmac_f32_e32 v35, 0xba800000, v2
	v_fmac_f32_e32 v5, 0xba800000, v2
	v_fmac_f32_e32 v31, 0xba800000, v2
	v_fmac_f32_e32 v3, 0xba800000, v2
	v_fmac_f32_e32 v7, 0xba800000, v2
	v_mul_f32_e32 v2, v32, v32
	v_mul_f32_e32 v4, v34, v34
	v_pk_add_f32 v[44:45], v[88:89], v[44:45]
	v_pk_add_f32 v[42:43], v[42:43], v[48:49]
	v_pk_fma_f32 v[50:51], v[32:33], v[32:33], v[2:3] op_sel_hi:[1,1,0]
	v_pk_fma_f32 v[84:85], v[34:35], v[34:35], v[4:5] op_sel_hi:[1,1,0]
	v_pk_add_f32 v[44:45], v[44:45], v[44:45] op_sel_hi:[0,1]
	v_pk_add_f32 v[42:43], v[42:43], v[42:43] op_sel_hi:[0,1]
	v_mul_f32_e32 v50, v7, v7
	v_mul_f32_e32 v84, v3, v3
	v_mul_f32_e32 v44, v31, v31
	v_mul_f32_e32 v42, v5, v5
	v_pk_add_f32 v[46:47], v[50:51], v[84:85]
	v_pk_add_f32 v[42:43], v[44:45], v[42:43]
	s_nop 0
	v_pk_add_f32 v[42:43], v[46:47], v[42:43]
	s_nop 0
	v_add_f32_e32 v2, v42, v43
	ds_bpermute_b32 v4, v57, v2
	v_or_b32_e32 v42, 1, v36
	v_ashrrev_i32_e32 v43, 31, v42
	v_lshlrev_b64 v[42:43], 11, v[42:43]
	v_lshl_add_u64 v[42:43], v[8:9], 0, v[42:43]
	s_waitcnt lgkmcnt(0)
	v_add_f32_e32 v2, v2, v4
	ds_bpermute_b32 v4, v58, v2
	global_load_dwordx2 v[44:45], v[42:43], off
	global_load_dwordx2 v[46:47], v[42:43], off offset:512
	global_load_dwordx2 v[50:51], v[42:43], off offset:1024
	global_load_dwordx2 v[48:49], v[42:43], off offset:1536
	v_lshlrev_b64 v[36:37], 10, v[36:37]
	s_waitcnt lgkmcnt(0)
	v_add_f32_e32 v2, v2, v4
	ds_bpermute_b32 v4, v59, v2
	s_waitcnt lgkmcnt(0)
	v_add_f32_e32 v2, v2, v4
	ds_bpermute_b32 v4, v60, v2
	s_waitcnt lgkmcnt(0)
	v_add_f32_e32 v2, v2, v4
	ds_bpermute_b32 v4, v61, v2
	s_waitcnt lgkmcnt(0)
	v_add_f32_e32 v2, v2, v4
	ds_bpermute_b32 v4, v62, v2
	s_waitcnt lgkmcnt(0)
	v_add_f32_e32 v2, v2, v4
	v_fmamk_f32 v2, v2, 0x3a800000, v71
	v_mul_f32_e32 v4, 0x4b800000, v2
	v_cmp_gt_f32_e32 vcc, s14, v2
	s_nop 1
	v_cndmask_b32_e32 v2, v2, v4, vcc
	v_rsq_f32_e32 v2, v2
	s_nop 0
	v_mul_f32_e32 v4, 0x45800000, v2
	v_cndmask_b32_e32 v6, v2, v4, vcc
	v_pk_mul_f32 v[40:41], v[40:41], v[6:7] op_sel_hi:[1,0]
	v_pk_mul_f32 v[42:43], v[82:83], v[6:7] op_sel_hi:[1,0]
	v_accvgpr_read_b32 v52, a8
	v_accvgpr_read_b32 v53, a9
	v_accvgpr_read_b32 v54, a10
	v_accvgpr_read_b32 v55, a11
	v_accvgpr_read_b32 v78, a12
	v_accvgpr_read_b32 v79, a13
	v_accvgpr_read_b32 v80, a14
	v_accvgpr_read_b32 v81, a15
	s_waitcnt vmcnt(4)
	v_pk_fma_f32 v[40:41], v[52:53], v[40:41], v[78:79]
	v_pk_fma_f32 v[82:83], v[54:55], v[42:43], v[80:81]
	v_cvt_pk_bf16_f32 v42, v40, v41
	v_mov_b32_e32 v2, 0
	v_cvt_pk_bf16_f32 v43, v82, v83
	global_store_dwordx2 v[0:1], v[42:43], off
	v_accvgpr_read_b32 v52, a16
	v_accvgpr_read_b32 v53, a17
	v_accvgpr_read_b32 v54, a18
	v_accvgpr_read_b32 v55, a19
	v_accvgpr_read_b32 v78, a20
	v_accvgpr_read_b32 v79, a21
	v_accvgpr_read_b32 v80, a22
	v_accvgpr_read_b32 v81, a23
	v_lshl_add_u64 v[42:43], v[28:29], 0, v[36:37]
	v_pk_mul_f32 v[32:33], v[32:33], v[6:7] op_sel_hi:[1,0]
	v_pk_mul_f32 v[34:35], v[34:35], v[6:7] op_sel_hi:[1,0]
	v_mov_b32_e32 v4, v31
	v_pk_mul_f32 v[4:5], v[4:5], v[6:7] op_sel_hi:[1,0]
	s_waitcnt vmcnt(1)
	v_and_b32_e32 v31, 0xffff0000, v48
	v_pk_add_f32 v[52:53], v[52:53], 1.0 op_sel_hi:[1,0]
	v_pk_add_f32 v[36:37], v[54:55], 1.0 op_sel_hi:[1,0]
	v_pk_fma_f32 v[52:53], v[52:53], v[40:41], v[78:79]
	v_pk_fma_f32 v[54:55], v[36:37], v[82:83], v[80:81]
	v_cvt_pk_fp8_f32 v2, v52, v53
	v_pk_mul_f32 v[36:37], v[38:39], v[6:7] op_sel_hi:[1,0]
	v_cvt_pk_fp8_f32 v2, v54, v55 op_sel:[0,0,1]
	global_store_dword v[42:43], v2, off
	v_accvgpr_read_b32 v78, a24
	v_accvgpr_read_b32 v79, a25
	v_accvgpr_read_b32 v80, a26
	v_accvgpr_read_b32 v81, a27
	v_accvgpr_read_b32 v82, a28
	v_accvgpr_read_b32 v83, a29
	v_accvgpr_read_b32 v84, a30
	v_accvgpr_read_b32 v85, a31
	v_pk_mul_f32 v[38:39], v[86:87], v[6:7] op_sel_hi:[1,0]
	ds_write_b128 v66, v[52:55]
	v_mov_b32_e32 v2, 0
	v_pk_fma_f32 v[40:41], v[80:81], v[38:39], v[84:85]
	v_pk_fma_f32 v[78:79], v[78:79], v[36:37], v[82:83]
	s_nop 0
	v_cvt_pk_bf16_f32 v36, v78, v79
	v_cvt_pk_bf16_f32 v37, v40, v41
	global_store_dwordx2 v[0:1], v[36:37], off offset:512
	v_accvgpr_read_b32 v36, a32
	v_accvgpr_read_b32 v37, a33
	v_accvgpr_read_b32 v38, a34
	v_accvgpr_read_b32 v39, a35
	s_nop 0
	v_accvgpr_read_b32 v52, a36
	v_accvgpr_read_b32 v53, a37
	v_accvgpr_read_b32 v54, a38
	v_accvgpr_read_b32 v55, a39
	v_pk_add_f32 v[36:37], v[36:37], 1.0 op_sel_hi:[1,0]
	v_pk_add_f32 v[38:39], v[38:39], 1.0 op_sel_hi:[1,0]
	v_pk_fma_f32 v[36:37], v[36:37], v[78:79], v[52:53]
	v_pk_fma_f32 v[38:39], v[38:39], v[40:41], v[54:55]
	v_cvt_pk_fp8_f32 v2, v36, v37
	s_nop 0
	v_cvt_pk_fp8_f32 v2, v38, v39 op_sel:[0,0,1]
	global_store_dword v[42:43], v2, off offset:256
	v_accvgpr_read_b32 v52, a40
	v_accvgpr_read_b32 v53, a41
	v_accvgpr_read_b32 v54, a42
	v_accvgpr_read_b32 v55, a43
	v_accvgpr_read_b32 v78, a44
	v_accvgpr_read_b32 v79, a45
	v_accvgpr_read_b32 v80, a46
	v_accvgpr_read_b32 v81, a47
	ds_write_b128 v66, v[36:39] offset:1024
	v_mov_b32_e32 v2, 0
	v_pk_fma_f32 v[40:41], v[34:35], v[54:55], v[80:81]
	v_pk_fma_f32 v[52:53], v[32:33], v[52:53], v[78:79]
	s_nop 0
	v_cvt_pk_bf16_f32 v32, v52, v53
	v_cvt_pk_bf16_f32 v33, v40, v41
	global_store_dwordx2 v[0:1], v[32:33], off offset:1024
	v_accvgpr_read_b32 v32, a48
	v_accvgpr_read_b32 v33, a49
	v_accvgpr_read_b32 v34, a50
	v_accvgpr_read_b32 v35, a51
	s_nop 0
	v_accvgpr_read_b32 v36, a52
	v_accvgpr_read_b32 v37, a53
	v_accvgpr_read_b32 v38, a54
	v_accvgpr_read_b32 v39, a55
	v_pk_add_f32 v[32:33], v[32:33], 1.0 op_sel_hi:[1,0]
	v_pk_add_f32 v[34:35], v[34:35], 1.0 op_sel_hi:[1,0]
	v_pk_fma_f32 v[32:33], v[52:53], v[32:33], v[36:37]
	v_pk_fma_f32 v[34:35], v[40:41], v[34:35], v[38:39]
	v_cvt_pk_fp8_f32 v2, v32, v33
	v_lshlrev_b32_e32 v38, 16, v50
	v_cvt_pk_fp8_f32 v2, v34, v35 op_sel:[0,0,1]
	global_store_dword v[42:43], v2, off offset:512
	v_accvgpr_read_b32 v78, a56
	v_accvgpr_read_b32 v79, a57
	v_accvgpr_read_b32 v80, a58
	v_accvgpr_read_b32 v81, a59
	v_accvgpr_read_b32 v82, a60
	v_accvgpr_read_b32 v83, a61
	v_accvgpr_read_b32 v84, a62
	v_accvgpr_read_b32 v85, a63
	v_mov_b32_e32 v2, v7
	v_pk_mul_f32 v[2:3], v[2:3], v[6:7] op_sel_hi:[1,0]
	ds_write_b128 v66, v[32:35] offset:2048
	v_and_b32_e32 v39, 0xffff0000, v50
	v_lshlrev_b32_e32 v40, 16, v51
	v_and_b32_e32 v41, 0xffff0000, v51
	v_lshlrev_b32_e32 v35, 16, v48
	v_lshlrev_b32_e32 v37, 16, v49
	v_and_b32_e32 v33, 0xffff0000, v49
	v_lshlrev_b32_e32 v49, 16, v45
	v_lshlrev_b32_e32 v48, 16, v44
	v_and_b32_e32 v51, 0xffff0000, v45
	v_and_b32_e32 v50, 0xffff0000, v44
	v_lshlrev_b32_e32 v45, 16, v47
	v_lshlrev_b32_e32 v44, 16, v46
	v_and_b32_e32 v47, 0xffff0000, v47
	v_and_b32_e32 v46, 0xffff0000, v46
	v_add_f32_e32 v36, v38, v39
	v_add_f32_e32 v32, v40, v41
	v_pk_fma_f32 v[52:53], v[4:5], v[80:81], v[84:85]
	v_pk_fma_f32 v[54:55], v[2:3], v[78:79], v[82:83]
	v_pk_add_f32 v[78:79], v[48:49], v[50:51]
	v_cvt_pk_bf16_f32 v2, v54, v55
	v_cvt_pk_bf16_f32 v3, v52, v53
	global_store_dwordx2 v[0:1], v[2:3], off offset:1536
	v_accvgpr_read_b32 v0, a64
	v_accvgpr_read_b32 v1, a65
	v_accvgpr_read_b32 v2, a66
	v_accvgpr_read_b32 v3, a67
	v_pk_add_f32 v[80:81], v[44:45], v[46:47]
	v_accvgpr_read_b32 v4, a68
	v_accvgpr_read_b32 v5, a69
	v_accvgpr_read_b32 v6, a70
	v_accvgpr_read_b32 v7, a71
	v_add_f32_e32 v30, v78, v79
	v_pk_add_f32 v[78:79], v[80:81], v[80:81] op_sel:[0,1] op_sel_hi:[1,0]
	v_add_f32_e32 v34, 0, v30
	v_mov_b32_e32 v79, v31
	v_pk_add_f32 v[80:81], v[36:37], v[32:33]
	v_pk_add_f32 v[78:79], v[34:35], v[78:79]
	v_mov_b32_e32 v34, 0
	v_pk_add_f32 v[78:79], v[78:79], v[80:81]
	v_pk_add_f32 v[0:1], v[0:1], 1.0 op_sel_hi:[1,0]
	v_add_f32_e32 v30, v78, v79
	ds_bpermute_b32 v32, v57, v30
	v_pk_add_f32 v[2:3], v[2:3], 1.0 op_sel_hi:[1,0]
	v_pk_fma_f32 v[78:79], v[54:55], v[0:1], v[4:5]
	v_pk_fma_f32 v[80:81], v[52:53], v[2:3], v[6:7]
	v_cvt_pk_fp8_f32 v34, v78, v79
	s_waitcnt lgkmcnt(0)
	v_add_f32_e32 v30, v30, v32
	ds_bpermute_b32 v32, v58, v30
	v_cvt_pk_fp8_f32 v34, v80, v81 op_sel:[0,0,1]
	global_store_dword v[42:43], v34, off offset:768
	v_accvgpr_read_b32 v52, a8
	v_accvgpr_read_b32 v53, a9
	v_accvgpr_read_b32 v54, a10
	v_accvgpr_read_b32 v55, a11
	v_accvgpr_read_b32 v82, a12
	v_accvgpr_read_b32 v83, a13
	v_accvgpr_read_b32 v84, a14
	v_accvgpr_read_b32 v85, a15
	ds_write_b128 v66, v[78:81] offset:3072
	s_waitcnt lgkmcnt(1)
	v_add_f32_e32 v30, v30, v32
	ds_bpermute_b32 v32, v59, v30
	s_waitcnt lgkmcnt(0)
	v_add_f32_e32 v30, v30, v32
	ds_bpermute_b32 v32, v60, v30
	s_waitcnt lgkmcnt(0)
	v_add_f32_e32 v30, v30, v32
	ds_bpermute_b32 v32, v61, v30
	s_waitcnt lgkmcnt(0)
	v_add_f32_e32 v30, v30, v32
	ds_bpermute_b32 v32, v62, v30
	s_waitcnt lgkmcnt(0)
	v_add_f32_e32 v30, v30, v32
	v_fmac_f32_e32 v50, 0xba800000, v30
	v_fmac_f32_e32 v51, 0xba800000, v30
	v_fmac_f32_e32 v49, 0xba800000, v30
	v_fmac_f32_e32 v46, 0xba800000, v30
	v_fmac_f32_e32 v47, 0xba800000, v30
	v_fmac_f32_e32 v45, 0xba800000, v30
	v_fmac_f32_e32 v48, 0xba800000, v30
	v_fmac_f32_e32 v44, 0xba800000, v30
	v_fmac_f32_e32 v38, 0xba800000, v30
	v_fmac_f32_e32 v40, 0xba800000, v30
	v_mov_b32_e32 v0, v49
	v_mov_b32_e32 v1, v51
	v_mov_b32_e32 v49, v50
	v_mov_b32_e32 v6, v45
	v_mov_b32_e32 v7, v47
	v_mov_b32_e32 v45, v46
	v_fmac_f32_e32 v39, 0xba800000, v30
	v_fmac_f32_e32 v41, 0xba800000, v30
	v_mul_f32_e32 v2, v38, v38
	v_mul_f32_e32 v4, v40, v40
	v_pk_mul_f32 v[42:43], v[0:1], v[0:1]
	v_pk_mul_f32 v[46:47], v[48:49], v[48:49]
	v_pk_mul_f32 v[50:51], v[6:7], v[6:7]
	v_pk_mul_f32 v[86:87], v[44:45], v[44:45]
	v_fmac_f32_e32 v31, 0xba800000, v30
	v_fmac_f32_e32 v35, 0xba800000, v30
	v_pk_fma_f32 v[2:3], v[38:39], v[38:39], v[2:3] op_sel_hi:[1,1,0]
	v_pk_fma_f32 v[4:5], v[40:41], v[40:41], v[4:5] op_sel_hi:[1,1,0]
	v_pk_mov_b32 v[88:89], v[46:47], v[42:43] op_sel:[1,0]
	v_mov_b32_e32 v47, v43
	v_pk_mov_b32 v[42:43], v[86:87], v[50:51] op_sel:[1,0]
	v_mov_b32_e32 v87, v51
	v_mul_f32_e32 v2, v35, v35
	v_mul_f32_e32 v4, v31, v31
	v_pk_add_f32 v[46:47], v[88:89], v[46:47]
	v_pk_add_f32 v[42:43], v[42:43], v[86:87]
	v_fmac_f32_e32 v33, 0xba800000, v30
	v_fmac_f32_e32 v37, 0xba800000, v30
	v_pk_add_f32 v[2:3], v[2:3], v[4:5]
	v_pk_add_f32 v[4:5], v[46:47], v[46:47] op_sel_hi:[0,1]
	v_pk_add_f32 v[42:43], v[42:43], v[42:43] op_sel_hi:[0,1]
	v_mul_f32_e32 v4, v37, v37
	v_mul_f32_e32 v42, v33, v33
	v_pk_add_f32 v[4:5], v[4:5], v[42:43]
	v_add_u32_e32 v42, s16, v67
	v_pk_add_f32 v[2:3], v[2:3], v[4:5]
	v_ashrrev_i32_e32 v43, 31, v42
	v_add_f32_e32 v2, v2, v3
	ds_bpermute_b32 v3, v57, v2
	v_mov_b32_e32 v30, v35
	v_mov_b32_e32 v32, v37
	s_waitcnt lgkmcnt(0)
	v_add_f32_e32 v2, v2, v3
	ds_bpermute_b32 v3, v58, v2
	s_waitcnt lgkmcnt(0)
	v_add_f32_e32 v2, v2, v3
	ds_bpermute_b32 v3, v59, v2
	s_waitcnt lgkmcnt(0)
	v_add_f32_e32 v2, v2, v3
	ds_bpermute_b32 v3, v60, v2
	s_waitcnt lgkmcnt(0)
	v_add_f32_e32 v2, v2, v3
	ds_bpermute_b32 v3, v61, v2
	s_waitcnt lgkmcnt(0)
	v_add_f32_e32 v2, v2, v3
	ds_bpermute_b32 v3, v62, v2
	s_waitcnt lgkmcnt(0)
	v_add_f32_e32 v2, v2, v3
	v_fmamk_f32 v2, v2, 0x3a800000, v71
	v_mul_f32_e32 v3, 0x4b800000, v2
	v_cmp_gt_f32_e32 vcc, s14, v2
	s_nop 1
	v_cndmask_b32_e32 v2, v2, v3, vcc
	v_rsq_f32_e32 v4, v2
	v_lshlrev_b64 v[2:3], 11, v[42:43]
	v_lshl_add_u64 v[2:3], v[8:9], 0, v[2:3]
	v_mul_f32_e32 v5, 0x45800000, v4
	v_cndmask_b32_e32 v4, v4, v5, vcc
	v_pk_mul_f32 v[46:47], v[48:49], v[4:5] op_sel_hi:[1,0]
	v_pk_mul_f32 v[0:1], v[0:1], v[4:5] op_sel_hi:[1,0]
	v_pk_fma_f32 v[78:79], v[52:53], v[46:47], v[82:83]
	v_pk_fma_f32 v[54:55], v[54:55], v[0:1], v[84:85]
	v_cvt_pk_bf16_f32 v0, v78, v79
	v_mov_b32_e32 v5, 0
	v_cvt_pk_bf16_f32 v1, v54, v55
	global_store_dwordx2 v[2:3], v[0:1], off
	v_accvgpr_read_b32 v46, a16
	v_accvgpr_read_b32 v47, a17
	v_accvgpr_read_b32 v48, a18
	v_accvgpr_read_b32 v49, a19
	v_accvgpr_read_b32 v50, a20
	v_accvgpr_read_b32 v51, a21
	v_accvgpr_read_b32 v52, a22
	v_accvgpr_read_b32 v53, a23
	v_lshlrev_b64 v[0:1], 10, v[42:43]
	v_lshl_add_u64 v[0:1], v[28:29], 0, v[0:1]
	v_pk_add_f32 v[46:47], v[46:47], 1.0 op_sel_hi:[1,0]
	v_pk_add_f32 v[42:43], v[48:49], 1.0 op_sel_hi:[1,0]
	v_pk_fma_f32 v[46:47], v[46:47], v[78:79], v[50:51]
	v_pk_fma_f32 v[48:49], v[42:43], v[54:55], v[52:53]
	v_cvt_pk_fp8_f32 v5, v46, v47
	s_nop 0
	v_cvt_pk_fp8_f32 v5, v48, v49 op_sel:[0,0,1]
	global_store_dword v[0:1], v5, off
	v_accvgpr_read_b32 v50, a24
	v_accvgpr_read_b32 v51, a25
	v_accvgpr_read_b32 v52, a26
	v_accvgpr_read_b32 v53, a27
	v_accvgpr_read_b32 v78, a28
	v_accvgpr_read_b32 v79, a29
	v_accvgpr_read_b32 v80, a30
	v_accvgpr_read_b32 v81, a31
	v_pk_mul_f32 v[42:43], v[44:45], v[4:5] op_sel_hi:[1,0]
	v_pk_mul_f32 v[6:7], v[6:7], v[4:5] op_sel_hi:[1,0]
	ds_write_b128 v68, v[46:49]
	v_mov_b32_e32 v5, 0
	v_pk_fma_f32 v[6:7], v[52:53], v[6:7], v[80:81]
	v_pk_fma_f32 v[50:51], v[50:51], v[42:43], v[78:79]
	s_nop 0
	v_cvt_pk_bf16_f32 v42, v50, v51
	v_cvt_pk_bf16_f32 v43, v6, v7
	global_store_dwordx2 v[2:3], v[42:43], off offset:512
	v_accvgpr_read_b32 v42, a32
	v_accvgpr_read_b32 v43, a33
	v_accvgpr_read_b32 v44, a34
	v_accvgpr_read_b32 v45, a35
	s_nop 0
	v_accvgpr_read_b32 v46, a36
	v_accvgpr_read_b32 v47, a37
	v_accvgpr_read_b32 v48, a38
	v_accvgpr_read_b32 v49, a39
	v_pk_add_f32 v[42:43], v[42:43], 1.0 op_sel_hi:[1,0]
	v_pk_add_f32 v[44:45], v[44:45], 1.0 op_sel_hi:[1,0]
	v_pk_fma_f32 v[42:43], v[42:43], v[50:51], v[46:47]
	v_pk_fma_f32 v[44:45], v[44:45], v[6:7], v[48:49]
	v_cvt_pk_fp8_f32 v5, v42, v43
	s_nop 0
	v_cvt_pk_fp8_f32 v5, v44, v45 op_sel:[0,0,1]
	global_store_dword v[0:1], v5, off offset:256
	v_accvgpr_read_b32 v46, a40
	v_accvgpr_read_b32 v47, a41
	v_accvgpr_read_b32 v48, a42
	v_accvgpr_read_b32 v49, a43
	v_accvgpr_read_b32 v50, a44
	v_accvgpr_read_b32 v51, a45
	v_accvgpr_read_b32 v52, a46
	v_accvgpr_read_b32 v53, a47
	v_pk_mul_f32 v[6:7], v[38:39], v[4:5] op_sel_hi:[1,0]
	v_pk_mul_f32 v[38:39], v[40:41], v[4:5] op_sel_hi:[1,0]
	ds_write_b128 v68, v[42:45] offset:1024
	v_mov_b32_e32 v5, 0
	v_pk_fma_f32 v[48:49], v[38:39], v[48:49], v[52:53]
	v_pk_fma_f32 v[6:7], v[6:7], v[46:47], v[50:51]
	s_nop 0
	v_cvt_pk_bf16_f32 v38, v6, v7
	v_cvt_pk_bf16_f32 v39, v48, v49
	global_store_dwordx2 v[2:3], v[38:39], off offset:1024
	v_accvgpr_read_b32 v38, a48
	v_accvgpr_read_b32 v39, a49
	v_accvgpr_read_b32 v40, a50
	v_accvgpr_read_b32 v41, a51
	s_nop 0
	v_accvgpr_read_b32 v42, a52
	v_accvgpr_read_b32 v43, a53
	v_accvgpr_read_b32 v44, a54
	v_accvgpr_read_b32 v45, a55
	v_pk_add_f32 v[38:39], v[38:39], 1.0 op_sel_hi:[1,0]
	v_pk_add_f32 v[40:41], v[40:41], 1.0 op_sel_hi:[1,0]
	v_pk_fma_f32 v[38:39], v[6:7], v[38:39], v[42:43]
	v_pk_fma_f32 v[40:41], v[48:49], v[40:41], v[44:45]
	v_cvt_pk_fp8_f32 v5, v38, v39
	s_nop 0
	v_cvt_pk_fp8_f32 v5, v40, v41 op_sel:[0,0,1]
	global_store_dword v[0:1], v5, off offset:512
	v_accvgpr_read_b32 v42, a56
	v_accvgpr_read_b32 v43, a57
	v_accvgpr_read_b32 v44, a58
	v_accvgpr_read_b32 v45, a59
	v_accvgpr_read_b32 v46, a60
	v_accvgpr_read_b32 v47, a61
	v_accvgpr_read_b32 v48, a62
	v_accvgpr_read_b32 v49, a63
	v_pk_mul_f32 v[6:7], v[30:31], v[4:5] op_sel_hi:[1,0]
	v_pk_mul_f32 v[4:5], v[32:33], v[4:5] op_sel_hi:[1,0]
	ds_write_b128 v68, v[38:41] offset:2048
	v_mov_b32_e32 v38, 0
	v_pk_fma_f32 v[34:35], v[4:5], v[44:45], v[48:49]
	v_pk_fma_f32 v[36:37], v[6:7], v[42:43], v[46:47]
	s_nop 0
	v_cvt_pk_bf16_f32 v4, v36, v37
	v_cvt_pk_bf16_f32 v5, v34, v35
	global_store_dwordx2 v[2:3], v[4:5], off offset:1536
	v_accvgpr_read_b32 v4, a64
	v_accvgpr_read_b32 v5, a65
	v_accvgpr_read_b32 v6, a66
	v_accvgpr_read_b32 v7, a67
	s_nop 0
	v_accvgpr_read_b32 v30, a68
	v_accvgpr_read_b32 v31, a69
	v_accvgpr_read_b32 v32, a70
	v_accvgpr_read_b32 v33, a71
	v_mov_b32_e32 v2, v70
	v_mov_b32_e32 v3, v69
	v_pk_add_f32 v[6:7], v[6:7], 1.0 op_sel_hi:[1,0]
	v_pk_add_f32 v[4:5], v[4:5], 1.0 op_sel_hi:[1,0]
	v_pk_fma_f32 v[6:7], v[34:35], v[6:7], v[32:33]
	v_pk_fma_f32 v[4:5], v[36:37], v[4:5], v[30:31]
	s_nop 0
	v_cvt_pk_fp8_f32 v38, v4, v5
	s_nop 0
	v_cvt_pk_fp8_f32 v38, v6, v7 op_sel:[0,0,1]
	ds_write_b128 v68, v[4:7] offset:3072
	global_store_dword v[0:1], v38, off offset:768
	s_waitcnt lgkmcnt(0)
	s_barrier
